# v18 + GEMM1 round-2 tiles swapped between context and latent token tiles (tile (tn2+8, tm^16) on workgroup j<128)
# baseline (speedup 1.0000x reference)
.LBB0_481:
	s_or_b64 exec, exec, s[8:9]
	s_add_i32 s80, s80, s76
	s_xor_b32 s80, s80, 16
	s_and_b64 vcc, exec, s[14:15]
	s_cbranch_vccnz .LBB0_1220

.LBB0_538:
	s_and_b32 s0, s80, 31
	s_xor_b64 s[62:63], s[12:13], -1
	s_lshl_b32 s64, s0, 8
	s_lshl_b32 s65, s0, 19
	s_ashr_i32 s16, s79, 5
	s_add_i32 s79, s79, s76
	s_xor_b32 s79, s79, 16
	s_cmpk_lt_i32 s79, 0x180
	s_cselect_b64 s[18:19], -1, 0
	s_cmpk_gt_i32 s79, 0x17f
	s_cselect_b64 s[14:15], -1, 0
	s_cmp_eq_u32 s16, 11
	s_cselect_b64 s[12:13], -1, 0
	s_cmp_lg_u32 s16, 11
	s_mov_b64 s[8:9], -1
	s_cbranch_scc0 .LBB0_1136
	s_lshl_b32 s2, s51, 8
	v_add_u32_e32 v0, s2, v221
	v_ashrrev_i32_e32 v1, 31, v0
	v_lshlrev_b64 v[2:3], 6, v[0:1]
	v_add_u32_e32 v0, 64, v0
	v_ashrrev_i32_e32 v1, 31, v0
	v_lshlrev_b64 v[0:1], 6, v[0:1]
	v_lshl_add_u64 v[2:3], s[4:5], 0, v[2:3]
	v_lshl_add_u64 v[0:1], s[4:5], 0, v[0:1]
	global_load_dwordx4 v[160:163], v[2:3], off
	global_load_dwordx4 v[156:159], v[2:3], off offset:16
	global_load_dwordx4 v[152:155], v[2:3], off offset:32
	global_load_dwordx4 v[82:85], v[2:3], off offset:48
	global_load_dwordx4 v[12:15], v[0:1], off
	global_load_dwordx4 v[8:11], v[0:1], off offset:16
	global_load_dwordx4 v[4:7], v[0:1], off offset:32
	s_nop 0
	global_load_dwordx4 v[0:3], v[0:1], off offset:48
	s_lshl_b32 s3, s16, 1
	v_readlane_b32 s0, v254, 23
	s_or_b32 s58, s3, s0
	s_lshl_b32 s0, s58, 7
	s_or_b32 s8, s0, s78
	s_cmp_lt_i32 s58, 23
	s_cselect_b64 s[26:27], -1, 0
	s_cmp_gt_i32 s58, 22
	v_mov_b32_e32 v80, 0
	s_cbranch_scc1 .LBB0_541
	s_add_i32 s0, s51, -16
	s_lshr_b32 s0, s0, 2
	s_add_i32 s0, s0, 1
	s_cmp_gt_u32 s51, 15
	s_cselect_b32 s0, s0, 0
	s_add_i32 s0, s0, s81
	s_ashr_i32 s9, s8, 31
	s_mul_hi_i32 s17, s0, 0x2e00
	s_mulk_i32 s0, 0x2e00
	v_readlane_b32 s28, v255, 15
	s_add_u32 s0, s28, s0
	v_readlane_b32 s28, v255, 16
	s_addc_u32 s17, s28, s17
	s_lshl_b64 s[28:29], s[8:9], 2
	s_add_u32 s28, s0, s28
	s_addc_u32 s29, s17, s29
	v_lshl_add_u64 v[16:17], v[188:189], 2, s[28:29]
	global_load_dword v80, v[16:17], off
